# attention FAST loop: drop m0 save/restore and nop pads around LDS-DMA (m0 written directly, address VALU as the wait state), drop 4 dead s_nop after empty asm pins
# speedup vs baseline: 1.0177x; 1.0049x over previous
.LBB0_413:
	s_mov_b32 s16, s26
	s_mov_b32 s2, s18
	s_mov_b32 s3, s24
	v_lshl_add_u32 v69, s17, 1, v232
	ds_read_b64_tr_b16 v[76:77], v69 offset:24576
	ds_read_b64_tr_b16 v[78:79], v69 offset:25088
	v_add_f32_e32 v72, v100, v101
	v_add_f32_e32 v72, v102, v72
	v_add_f32_e32 v72, v103, v72
	v_add_f32_e32 v72, v104, v72
	v_add_f32_e32 v72, v105, v72
	v_cvt_pk_bf16_f32 v160, v100, v101
	v_cvt_pk_bf16_f32 v161, v102, v103
	s_waitcnt lgkmcnt(9)
	v_mfma_f32_32x32x16_bf16 v[132:147], v[208:211], v[176:179], 0
	v_add_f32_e32 v72, v106, v72
	v_add_f32_e32 v72, v107, v72
	v_add_f32_e32 v72, v108, v72
	v_add_f32_e32 v72, v109, v72
	v_cvt_pk_bf16_f32 v162, v104, v105
	v_cvt_pk_bf16_f32 v163, v106, v107
	s_waitcnt lgkmcnt(8)
	v_mfma_f32_32x32x16_bf16 v[116:131], v[200:203], v[176:179], 0
	ds_read_b64_tr_b16 v[80:81], v69 offset:25600
	ds_read_b64_tr_b16 v[82:83], v69 offset:26112
	v_add_f32_e32 v72, v110, v72
	v_add_f32_e32 v72, v111, v72
	v_add_f32_e32 v72, v112, v72
	v_add_f32_e32 v72, v113, v72
	v_cvt_pk_bf16_f32 v156, v108, v109
	v_cvt_pk_bf16_f32 v157, v110, v111
	s_waitcnt lgkmcnt(9)
	v_mfma_f32_32x32x16_bf16 v[132:147], v[204:207], v[172:175], v[132:147]
	v_add_f32_e32 v72, v114, v72
	v_add_f32_e32 v72, v115, v72
	v_add_f32_e32 v72, v84, v72
	v_add_f32_e32 v72, v85, v72
	v_cvt_pk_bf16_f32 v158, v112, v113
	v_cvt_pk_bf16_f32 v159, v114, v115
	s_waitcnt lgkmcnt(8)
	v_mfma_f32_32x32x16_bf16 v[116:131], v[196:199], v[172:175], v[116:131]
	ds_read_b64_tr_b16 v[100:101], v69 offset:26624
	ds_read_b64_tr_b16 v[102:103], v69 offset:27136
	v_add_f32_e32 v72, v86, v72
	v_add_f32_e32 v72, v87, v72
	v_add_f32_e32 v72, v88, v72
	v_add_f32_e32 v72, v89, v72
	v_cvt_pk_bf16_f32 v152, v84, v85
	v_cvt_pk_bf16_f32 v153, v86, v87
	s_waitcnt lgkmcnt(9)
	v_mfma_f32_32x32x16_bf16 v[132:147], v[192:195], v[168:171], v[132:147]
	v_add_f32_e32 v72, v90, v72
	v_add_f32_e32 v72, v91, v72
	v_add_f32_e32 v72, v92, v72
	v_add_f32_e32 v72, v93, v72
	v_cvt_pk_bf16_f32 v154, v88, v89
	v_cvt_pk_bf16_f32 v155, v90, v91
	s_waitcnt lgkmcnt(8)
	v_mfma_f32_32x32x16_bf16 v[116:131], v[188:191], v[168:171], v[116:131]
	ds_read_b64_tr_b16 v[84:85], v69 offset:27648
	ds_read_b64_tr_b16 v[86:87], v69 offset:28160
	v_add_f32_e32 v72, v94, v72
	v_add_f32_e32 v72, v95, v72
	v_add_f32_e32 v72, v96, v72
	v_add_f32_e32 v72, v97, v72
	v_cvt_pk_bf16_f32 v148, v92, v93
	v_cvt_pk_bf16_f32 v149, v94, v95
	s_waitcnt lgkmcnt(9)
	v_mfma_f32_32x32x16_bf16 v[132:147], v[184:187], v[164:167], v[132:147]
	v_add_f32_e32 v72, v98, v72
	v_add_f32_e32 v72, v99, v72
	v_add_f32_e32 v72, 0, v72
	v_cvt_pk_bf16_f32 v150, v96, v97
	v_cvt_pk_bf16_f32 v151, v98, v99
	s_waitcnt lgkmcnt(8)
	v_mfma_f32_32x32x16_bf16 v[116:131], v[180:183], v[164:167], v[116:131]
	v_lshl_add_u64 v[74:75], v[0:1], 0, s[14:15]
	v_add_f32_e32 v68, v68, v72
	s_add_i32 m0, s24, s0
	v_lshl_add_u64 v[72:73], v[74:75], 0, s[76:77]
	global_load_lds_dwordx4 v[72:73], off
	s_lshl_b32 s17, s26, 1
	s_add_i32 s17, s17, s1
	s_mov_b32 m0, s17
	v_lshl_add_u64 v[72:73], v[70:71], 0, s[14:15]
	v_lshl_add_u64 v[88:89], v[72:73], 0, s[90:91]
	global_load_lds_dwordx4 v[88:89], off
	s_add_i32 m0, s17, 0x2000
	v_lshl_add_u64 v[88:89], v[72:73], 0, s[92:93]
	global_load_lds_dwordx4 v[88:89], off
	s_waitcnt lgkmcnt(6)
	v_mfma_f32_32x32x16_bf16 v[36:51], v[160:163], v[76:79], v[36:51]
	v_exp_f32_e32 v132, v132
	v_exp_f32_e32 v133, v133
	ds_read_b64_tr_b16 v[76:77], v69 offset:28672
	ds_read_b64_tr_b16 v[78:79], v69 offset:29184
	s_waitcnt lgkmcnt(6)
	v_mfma_f32_32x32x16_bf16 v[36:51], v[156:159], v[80:83], v[36:51]
	v_exp_f32_e32 v134, v134
	v_exp_f32_e32 v135, v135
	ds_read_b64_tr_b16 v[80:81], v69 offset:29696
	ds_read_b64_tr_b16 v[82:83], v69 offset:30208
	s_waitcnt lgkmcnt(6)
	v_mfma_f32_32x32x16_bf16 v[36:51], v[152:155], v[100:103], v[36:51]
	v_exp_f32_e32 v136, v136
	v_exp_f32_e32 v137, v137
	ds_read_b64_tr_b16 v[88:89], v69 offset:30720
	ds_read_b64_tr_b16 v[90:91], v69 offset:31232
	s_waitcnt lgkmcnt(6)
	v_mfma_f32_32x32x16_bf16 v[36:51], v[148:151], v[84:87], v[36:51]
	v_exp_f32_e32 v138, v138
	v_exp_f32_e32 v139, v139
	ds_read_b64_tr_b16 v[84:85], v69 offset:31744
	ds_read_b64_tr_b16 v[86:87], v69 offset:32256
	s_waitcnt lgkmcnt(6)
	v_mfma_f32_32x32x16_bf16 v[52:67], v[160:163], v[76:79], v[52:67]
	v_exp_f32_e32 v140, v140
	v_exp_f32_e32 v141, v141
	ds_read_b64_tr_b16 v[76:77], v69 offset:32768
	ds_read_b64_tr_b16 v[78:79], v69 offset:33280
	s_waitcnt lgkmcnt(6)
	v_mfma_f32_32x32x16_bf16 v[52:67], v[156:159], v[80:83], v[52:67]
	v_exp_f32_e32 v142, v142
	v_exp_f32_e32 v143, v143
	ds_read_b64_tr_b16 v[80:81], v69 offset:33792
	ds_read_b64_tr_b16 v[82:83], v69 offset:34304
	s_waitcnt lgkmcnt(6)
	v_mfma_f32_32x32x16_bf16 v[52:67], v[152:155], v[88:91], v[52:67]
	v_exp_f32_e32 v144, v144
	v_exp_f32_e32 v145, v145
	ds_read_b64_tr_b16 v[88:89], v69 offset:34816
	ds_read_b64_tr_b16 v[90:91], v69 offset:35328
	s_waitcnt lgkmcnt(6)
	v_mfma_f32_32x32x16_bf16 v[52:67], v[148:151], v[84:87], v[52:67]
	v_exp_f32_e32 v146, v146
	v_exp_f32_e32 v147, v147
	ds_read_b64_tr_b16 v[84:85], v69 offset:35840
	ds_read_b64_tr_b16 v[86:87], v69 offset:36352
	s_waitcnt lgkmcnt(6)
	v_mfma_f32_32x32x16_bf16 v[4:19], v[160:163], v[76:79], v[4:19]
	v_exp_f32_e32 v116, v116
	v_exp_f32_e32 v117, v117
	ds_read_b64_tr_b16 v[76:77], v69 offset:36864
	ds_read_b64_tr_b16 v[78:79], v69 offset:37376
	s_waitcnt lgkmcnt(6)
	v_mfma_f32_32x32x16_bf16 v[4:19], v[156:159], v[80:83], v[4:19]
	v_exp_f32_e32 v118, v118
	v_exp_f32_e32 v119, v119
	ds_read_b64_tr_b16 v[80:81], v69 offset:37888
	ds_read_b64_tr_b16 v[82:83], v69 offset:38400
	s_waitcnt lgkmcnt(6)
	v_mfma_f32_32x32x16_bf16 v[4:19], v[152:155], v[88:91], v[4:19]
	v_exp_f32_e32 v120, v120
	v_exp_f32_e32 v121, v121
	ds_read_b64_tr_b16 v[88:89], v69 offset:38912
	ds_read_b64_tr_b16 v[90:91], v69 offset:39424
	s_waitcnt lgkmcnt(6)
	v_mfma_f32_32x32x16_bf16 v[4:19], v[148:151], v[84:87], v[4:19]
	v_exp_f32_e32 v122, v122
	v_exp_f32_e32 v123, v123
	ds_read_b64_tr_b16 v[84:85], v69 offset:39936
	ds_read_b64_tr_b16 v[86:87], v69 offset:40448
	v_add_u32_e32 v69, s16, v230
	ds_read_b128 v[92:95], v69
	ds_read_b128 v[96:99], v69 offset:512
	s_waitcnt lgkmcnt(8)
	v_mfma_f32_32x32x16_bf16 v[20:35], v[160:163], v[76:79], v[20:35]
	v_exp_f32_e32 v124, v124
	v_exp_f32_e32 v125, v125
	ds_read_b128 v[76:79], v69 offset:2048
	ds_read_b128 v[180:183], v69 offset:2560
	s_waitcnt lgkmcnt(8)
	v_mfma_f32_32x32x16_bf16 v[20:35], v[156:159], v[80:83], v[20:35]
	v_exp_f32_e32 v126, v126
	v_exp_f32_e32 v127, v127
	ds_read_b128 v[80:83], v69 offset:4096
	ds_read_b128 v[184:187], v69 offset:4608
	s_waitcnt lgkmcnt(8)
	v_mfma_f32_32x32x16_bf16 v[20:35], v[152:155], v[88:91], v[20:35]
	v_exp_f32_e32 v128, v128
	v_exp_f32_e32 v129, v129
	ds_read_b128 v[188:191], v69 offset:6144
	ds_read_b128 v[192:195], v69 offset:6656
	s_waitcnt lgkmcnt(8)
	v_mfma_f32_32x32x16_bf16 v[20:35], v[148:151], v[84:87], v[20:35]
	v_exp_f32_e32 v130, v130
	v_exp_f32_e32 v131, v131
	s_waitcnt vmcnt(3) lgkmcnt(0)
	s_barrier
	s_add_i32 s17, s26, 0x2000
	s_cmpk_lg_i32 s26, 0x4000
	s_cselect_b32 s24, s17, 0
	v_lshl_add_u32 v69, s3, 1, v232
	ds_read_b64_tr_b16 v[196:197], v69 offset:24576
	ds_read_b64_tr_b16 v[198:199], v69 offset:25088
	s_waitcnt lgkmcnt(9)
	v_mfma_f32_32x32x16_bf16 v[100:115], v[92:95], v[176:179], 0
	v_add_f32_e32 v84, v132, v133
	v_add_f32_e32 v84, v134, v84
	v_add_f32_e32 v84, v135, v84
	v_add_f32_e32 v84, v136, v84
	v_add_f32_e32 v84, v137, v84
	v_cvt_pk_bf16_f32 v160, v132, v133
	v_cvt_pk_bf16_f32 v161, v134, v135
	v_add_f32_e32 v84, v138, v84
	v_add_f32_e32 v84, v139, v84
	v_add_f32_e32 v84, v140, v84
	v_add_f32_e32 v148, v141, v84
	s_waitcnt lgkmcnt(8)
	v_mfma_f32_32x32x16_bf16 v[84:99], v[96:99], v[176:179], 0
	v_cvt_pk_bf16_f32 v162, v136, v137
	v_cvt_pk_bf16_f32 v163, v138, v139
	ds_read_b64_tr_b16 v[132:133], v69 offset:25600
	ds_read_b64_tr_b16 v[134:135], v69 offset:26112
	s_waitcnt lgkmcnt(9)
	v_mfma_f32_32x32x16_bf16 v[100:115], v[76:79], v[172:175], v[100:115]
	v_add_f32_e32 v76, v142, v148
	v_add_f32_e32 v76, v143, v76
	v_add_f32_e32 v76, v144, v76
	v_add_f32_e32 v76, v145, v76
	v_cvt_pk_bf16_f32 v156, v140, v141
	v_cvt_pk_bf16_f32 v157, v142, v143
	s_waitcnt lgkmcnt(8)
	v_mfma_f32_32x32x16_bf16 v[84:99], v[180:183], v[172:175], v[84:99]
	v_add_f32_e32 v76, v146, v76
	v_add_f32_e32 v76, v147, v76
	v_add_f32_e32 v76, v116, v76
	v_add_f32_e32 v136, v117, v76
	v_cvt_pk_bf16_f32 v158, v144, v145
	v_cvt_pk_bf16_f32 v159, v146, v147
	ds_read_b64_tr_b16 v[76:77], v69 offset:26624
	ds_read_b64_tr_b16 v[78:79], v69 offset:27136
	s_waitcnt lgkmcnt(9)
	v_mfma_f32_32x32x16_bf16 v[100:115], v[80:83], v[168:171], v[100:115]
	v_add_f32_e32 v80, v118, v136
	v_add_f32_e32 v80, v119, v80
	v_add_f32_e32 v80, v120, v80
	v_add_f32_e32 v80, v121, v80
	v_cvt_pk_bf16_f32 v152, v116, v117
	v_cvt_pk_bf16_f32 v153, v118, v119
	s_waitcnt lgkmcnt(8)
	v_mfma_f32_32x32x16_bf16 v[84:99], v[184:187], v[168:171], v[84:99]
	v_add_f32_e32 v80, v122, v80
	v_add_f32_e32 v80, v123, v80
	v_add_f32_e32 v80, v124, v80
	v_add_f32_e32 v116, v125, v80
	v_cvt_pk_bf16_f32 v154, v120, v121
	v_cvt_pk_bf16_f32 v155, v122, v123
	ds_read_b64_tr_b16 v[80:81], v69 offset:27648
	ds_read_b64_tr_b16 v[82:83], v69 offset:28160
	s_waitcnt lgkmcnt(9)
	v_mfma_f32_32x32x16_bf16 v[100:115], v[188:191], v[164:167], v[100:115]
	v_add_f32_e32 v116, v126, v116
	v_add_f32_e32 v116, v127, v116
	v_add_f32_e32 v116, v128, v116
	v_add_f32_e32 v116, v129, v116
	v_cvt_pk_bf16_f32 v148, v124, v125
	v_cvt_pk_bf16_f32 v149, v126, v127
	s_waitcnt lgkmcnt(8)
	v_mfma_f32_32x32x16_bf16 v[84:99], v[192:195], v[164:167], v[84:99]
	v_add_f32_e32 v116, v130, v116
	v_add_f32_e32 v116, v131, v116
	v_add_f32_e32 v116, 0, v116
	v_cvt_pk_bf16_f32 v150, v128, v129
	v_cvt_pk_bf16_f32 v151, v130, v131
	s_add_i32 m0, s26, s0
	v_lshl_add_u64 v[74:75], v[74:75], 0, s[28:29]
	global_load_lds_dwordx4 v[74:75], off
	s_lshl_b32 s3, s24, 1
	s_add_i32 s3, s3, s1
	s_mov_b32 m0, s3
	v_lshl_add_u64 v[74:75], v[72:73], 0, s[66:67]
	global_load_lds_dwordx4 v[74:75], off
	s_add_i32 m0, s3, 0x2000
	v_lshl_add_u64 v[72:73], v[72:73], 0, s[72:73]
	global_load_lds_dwordx4 v[72:73], off
	v_add_f32_e32 v68, v68, v116
	s_waitcnt lgkmcnt(6)
	v_mfma_f32_32x32x16_bf16 v[36:51], v[160:163], v[196:199], v[36:51]
	v_exp_f32_e32 v100, v100
	v_exp_f32_e32 v101, v101
	ds_read_b64_tr_b16 v[72:73], v69 offset:28672
	ds_read_b64_tr_b16 v[74:75], v69 offset:29184
	s_waitcnt lgkmcnt(6)
	v_mfma_f32_32x32x16_bf16 v[36:51], v[156:159], v[132:135], v[36:51]
	v_exp_f32_e32 v102, v102
	v_exp_f32_e32 v103, v103
	ds_read_b64_tr_b16 v[116:117], v69 offset:29696
	ds_read_b64_tr_b16 v[118:119], v69 offset:30208
	s_waitcnt lgkmcnt(6)
	v_mfma_f32_32x32x16_bf16 v[36:51], v[152:155], v[76:79], v[36:51]
	v_exp_f32_e32 v104, v104
	v_exp_f32_e32 v105, v105
	ds_read_b64_tr_b16 v[76:77], v69 offset:30720
	ds_read_b64_tr_b16 v[78:79], v69 offset:31232
	s_waitcnt lgkmcnt(6)
	v_mfma_f32_32x32x16_bf16 v[36:51], v[148:151], v[80:83], v[36:51]
	v_exp_f32_e32 v106, v106
	v_exp_f32_e32 v107, v107
	ds_read_b64_tr_b16 v[80:81], v69 offset:31744
	ds_read_b64_tr_b16 v[82:83], v69 offset:32256
	s_waitcnt lgkmcnt(6)
	v_mfma_f32_32x32x16_bf16 v[52:67], v[160:163], v[72:75], v[52:67]
	v_exp_f32_e32 v108, v108
	v_exp_f32_e32 v109, v109
	ds_read_b64_tr_b16 v[72:73], v69 offset:32768
	ds_read_b64_tr_b16 v[74:75], v69 offset:33280
	s_waitcnt lgkmcnt(6)
	v_mfma_f32_32x32x16_bf16 v[52:67], v[156:159], v[116:119], v[52:67]
	v_exp_f32_e32 v110, v110
	v_exp_f32_e32 v111, v111
	ds_read_b64_tr_b16 v[116:117], v69 offset:33792
	ds_read_b64_tr_b16 v[118:119], v69 offset:34304
	s_waitcnt lgkmcnt(6)
	v_mfma_f32_32x32x16_bf16 v[52:67], v[152:155], v[76:79], v[52:67]
	v_exp_f32_e32 v112, v112
	v_exp_f32_e32 v113, v113
	ds_read_b64_tr_b16 v[76:77], v69 offset:34816
	ds_read_b64_tr_b16 v[78:79], v69 offset:35328
	s_waitcnt lgkmcnt(6)
	v_mfma_f32_32x32x16_bf16 v[52:67], v[148:151], v[80:83], v[52:67]
	v_exp_f32_e32 v114, v114
	v_exp_f32_e32 v115, v115
	ds_read_b64_tr_b16 v[80:81], v69 offset:35840
	ds_read_b64_tr_b16 v[82:83], v69 offset:36352
	s_waitcnt lgkmcnt(6)
	v_mfma_f32_32x32x16_bf16 v[4:19], v[160:163], v[72:75], v[4:19]
	v_exp_f32_e32 v84, v84
	v_exp_f32_e32 v85, v85
	ds_read_b64_tr_b16 v[72:73], v69 offset:36864
	ds_read_b64_tr_b16 v[74:75], v69 offset:37376
	s_waitcnt lgkmcnt(6)
	v_mfma_f32_32x32x16_bf16 v[4:19], v[156:159], v[116:119], v[4:19]
	v_exp_f32_e32 v86, v86
	v_exp_f32_e32 v87, v87
	ds_read_b64_tr_b16 v[116:117], v69 offset:37888
	ds_read_b64_tr_b16 v[118:119], v69 offset:38400
	s_waitcnt lgkmcnt(6)
	v_mfma_f32_32x32x16_bf16 v[4:19], v[152:155], v[76:79], v[4:19]
	v_exp_f32_e32 v88, v88
	v_exp_f32_e32 v89, v89
	ds_read_b64_tr_b16 v[76:77], v69 offset:38912
	ds_read_b64_tr_b16 v[78:79], v69 offset:39424
	s_waitcnt lgkmcnt(6)
	v_mfma_f32_32x32x16_bf16 v[4:19], v[148:151], v[80:83], v[4:19]
	v_exp_f32_e32 v90, v90
	v_exp_f32_e32 v91, v91
	ds_read_b64_tr_b16 v[80:81], v69 offset:39936
	ds_read_b64_tr_b16 v[82:83], v69 offset:40448
	v_add_u32_e32 v69, s24, v230
	ds_read_b128 v[208:211], v69
	ds_read_b128 v[200:203], v69 offset:512
	s_waitcnt lgkmcnt(8)
	v_mfma_f32_32x32x16_bf16 v[20:35], v[160:163], v[72:75], v[20:35]
	v_exp_f32_e32 v92, v92
	v_exp_f32_e32 v93, v93
	ds_read_b128 v[204:207], v69 offset:2048
	ds_read_b128 v[196:199], v69 offset:2560
	s_waitcnt lgkmcnt(8)
	v_mfma_f32_32x32x16_bf16 v[20:35], v[156:159], v[116:119], v[20:35]
	v_exp_f32_e32 v94, v94
	v_exp_f32_e32 v95, v95
	ds_read_b128 v[192:195], v69 offset:4096
	ds_read_b128 v[188:191], v69 offset:4608
	s_waitcnt lgkmcnt(8)
	v_mfma_f32_32x32x16_bf16 v[20:35], v[152:155], v[76:79], v[20:35]
	v_exp_f32_e32 v96, v96
	v_exp_f32_e32 v97, v97
	ds_read_b128 v[184:187], v69 offset:6144
	ds_read_b128 v[180:183], v69 offset:6656
	s_waitcnt lgkmcnt(8)
	v_mfma_f32_32x32x16_bf16 v[20:35], v[148:151], v[80:83], v[20:35]
	v_exp_f32_e32 v98, v98
	v_exp_f32_e32 v99, v99
	s_add_i32 s3, s24, 0x2000
	s_cmpk_lg_i32 s24, 0x4000
	s_cselect_b32 s26, s3, 0
	s_add_i32 s18, s2, 2
	s_waitcnt vmcnt(3) lgkmcnt(0)
	s_barrier
	s_add_u32 s14, s14, 0x20000
	s_addc_u32 s15, s15, 0
	s_cmp_ge_u32 s18, s21
	s_mov_b32 s17, s16
	s_cbranch_scc0 .LBB0_413
	s_add_i32 s64, s2, -3
	s_lshl_b64 s[12:13], s[12:13], 9
	s_add_i32 s2, s64, 1
	s_cmp_lt_u32 s2, s21
	s_cbranch_scc0 .LBB0_441
